# P3 loader waves: prefetch addresses kept in VGPR pairs and advanced by one 64-bit add per chunk instead of recomputed (12 64-bit multiply-adds + shifts per chunk)
# speedup vs baseline: 1.0153x; 1.0014x over previous
; __device__ __forceinline__ void rwkv_scan_prompt(const Params& p, LAS unsigned char* lds, int bh, int rq) {
;     ...
;     auto issue_chunk = [&](int c) {
; #pragma unroll
;         for (int i = 0; i < NPIECE; ++i) {
;             const int piece = ltid + 256 * i, tk = piece / 48, q = piece % 48, vec = q >> 3, c8 = q & 7;
;             pre[i] = *(const h16x8*)(OPSG + (((size_t)(rowbase + c * TC + tk) * 8 + h) * 6 + vec) * 64 + c8 * 8);
;         }
;         if (ltid < TC) prk = RKS[(size_t)(rowbase + c * TC + ltid) * 8 + h];
;     };
;     ...
;             if (c + 1 < NCH) store_chunk(buf ^ 1);
;             if (c + 2 < NCH) issue_chunk(c + 2);
.LBB0_355:
	s_cmp_gt_u32 s73, 61
	s_cbranch_scc1 .LBB0_335
	s_waitcnt vmcnt(0)
	s_cmp_lg_u32 s0, 0
	s_cbranch_scc1 .Lldp_inc
	s_waitcnt vmcnt(5)
	v_add_u32_e32 v0, s0, v158
	s_waitcnt vmcnt(3)
	v_add_u32_e32 v8, s0, v102
	s_waitcnt vmcnt(1)
	v_add_u32_e32 v16, s0, v106
	v_ashrrev_i32_e32 v1, 31, v0
	v_ashrrev_i32_e32 v9, 31, v8
	v_ashrrev_i32_e32 v17, 31, v16
	v_lshl_add_u64 v[0:1], v[0:1], 3, v[86:87]
	v_lshl_add_u64 v[8:9], v[8:9], 3, v[86:87]
	v_lshl_add_u64 v[16:17], v[16:17], 3, v[86:87]
	v_mad_u64_u32 v[2:3], s[78:79], v0, 6, v[60:61]
	v_mad_u64_u32 v[10:11], s[78:79], v8, 6, v[40:41]
	v_mad_u64_u32 v[18:19], s[78:79], v16, 6, v[92:93]
	v_mov_b32_e32 v0, v3
	v_mov_b32_e32 v8, v11
	v_mov_b32_e32 v16, v19
	v_mad_u64_u32 v[0:1], s[78:79], v1, 6, v[0:1]
	v_mad_u64_u32 v[8:9], s[78:79], v9, 6, v[8:9]
	v_mad_u64_u32 v[16:17], s[78:79], v17, 6, v[16:17]
	v_mov_b32_e32 v3, v0
	v_mov_b32_e32 v11, v8
	v_mov_b32_e32 v19, v16
	v_lshlrev_b64 v[0:1], 7, v[2:3]
	v_add_u32_e32 v2, s0, v157
	v_lshlrev_b64 v[8:9], 7, v[10:11]
	v_add_u32_e32 v10, s0, v104
	v_lshlrev_b64 v[16:17], 7, v[18:19]
	v_add_u32_e32 v18, s0, v156
	v_ashrrev_i32_e32 v3, 31, v2
	v_ashrrev_i32_e32 v11, 31, v10
	v_ashrrev_i32_e32 v19, 31, v18
	v_lshl_add_u64 v[2:3], v[2:3], 3, v[86:87]
	v_lshl_add_u64 v[10:11], v[10:11], 3, v[86:87]
	v_lshl_add_u64 v[18:19], v[18:19], 3, v[86:87]
	v_mad_u64_u32 v[4:5], s[78:79], v2, 6, v[42:43]
	v_mad_u64_u32 v[12:13], s[78:79], v10, 6, v[90:91]
	s_waitcnt vmcnt(0)
	v_mad_u64_u32 v[20:21], s[78:79], v18, 6, v[58:59]
	v_mov_b32_e32 v2, v5
	v_mov_b32_e32 v10, v13
	v_mov_b32_e32 v18, v21
	v_mad_u64_u32 v[2:3], s[78:79], v3, 6, v[2:3]
	v_mad_u64_u32 v[10:11], s[78:79], v11, 6, v[10:11]
	v_mad_u64_u32 v[18:19], s[78:79], v19, 6, v[18:19]
	v_mov_b32_e32 v5, v2
	v_mov_b32_e32 v13, v10
	v_mov_b32_e32 v21, v18
	v_lshlrev_b64 v[2:3], 7, v[4:5]
	v_lshlrev_b64 v[10:11], 7, v[12:13]
	v_lshlrev_b64 v[18:19], 7, v[20:21]
	v_lshl_add_u64 v[0:1], v[80:81], 0, v[0:1]
	v_lshl_add_u64 v[4:5], v[70:71], 0, v[2:3]
	v_lshl_add_u64 v[8:9], v[94:95], 0, v[8:9]
	v_lshl_add_u64 v[12:13], v[96:97], 0, v[10:11]
	v_lshl_add_u64 v[16:17], v[98:99], 0, v[16:17]
	v_lshl_add_u64 v[20:21], v[78:79], 0, v[18:19]
	v_mov_b32_e32 v208, v0
	v_mov_b32_e32 v209, v1
	v_mov_b32_e32 v210, v4
	v_mov_b32_e32 v211, v5
	v_mov_b32_e32 v212, v8
	v_mov_b32_e32 v213, v9
	v_mov_b32_e32 v214, v12
	v_mov_b32_e32 v215, v13
	v_mov_b32_e32 v216, v16
	v_mov_b32_e32 v217, v17
	v_mov_b32_e32 v220, v20
	v_mov_b32_e32 v221, v21
	s_branch .Lldp_go
.Lldp_inc:
	s_mov_b32 s100, 0x30000
	s_mov_b32 s101, 0
	v_lshl_add_u64 v[208:209], v[208:209], 0, s[100:101]
	v_lshl_add_u64 v[210:211], v[210:211], 0, s[100:101]
	v_lshl_add_u64 v[212:213], v[212:213], 0, s[100:101]
	v_lshl_add_u64 v[214:215], v[214:215], 0, s[100:101]
	v_lshl_add_u64 v[216:217], v[216:217], 0, s[100:101]
	v_lshl_add_u64 v[220:221], v[220:221], 0, s[100:101]
.Lldp_go:
	global_load_dwordx4 v[0:3], v[208:209], off
	global_load_dwordx4 v[4:7], v[210:211], off
	global_load_dwordx4 v[8:11], v[212:213], off
	global_load_dwordx4 v[12:15], v[214:215], off
	global_load_dwordx4 v[16:19], v[216:217], off
	global_load_dwordx4 v[20:23], v[220:221], off
	s_and_saveexec_b64 s[78:79], s[56:57]
	s_cbranch_execz .LBB0_334
	v_add_u32_e32 v28, s0, v155
	v_ashrrev_i32_e32 v29, 31, v28
	v_lshlrev_b64 v[28:29], 5, v[28:29]
	v_lshl_add_u64 v[28:29], v[100:101], 0, v[28:29]
	global_load_dword v103, v[28:29], off
	s_branch .LBB0_334
